# v52 (permlane epilogue reductions) + GEMM accumulator zeroing with v_mov_b64 pairs instead of 128 v_mov_b32 per tile
# speedup vs baseline: 1.0020x; 1.0020x over previous
;     __host__ __device__ bool next(int i, Unit& u) const { const bool ok = StaticOrder::next(i >> 1, u); u.z = i & 1; return ok; }
; template <class Epi, class Sched, bool ALIGN_EPI = true, bool SP2 = true>
; __device__ __forceinline__ void gemm_phase(LAS unsigned char* lds, const Gemm g, const Sched& S, const Epi& E) {
;     ...
;         const bool has_next = S.next(ui + 1, nxt);
;         const char* nA = has_next ? PG8_ABASE(nxt) : cA; const char* nB = has_next ? PG8_BBASE(nxt) : cB;
;         for (int t = 0; t < nt; t += 2) {
;             const bool last = (t == nt - 2);
;             const char* a1 = cA + (size_t)(t + 1) * kstep;
;             const char* a2 = last ? nA : cA + (size_t)(t + 2) * kstep; const char* b2 = last ? nB : cB + (size_t)(t + 2) * kstep;
;             const char* a3 = a2 + kstep; const char* b3 = b2 + kstep;
;     ...
;         for (int a = 0; a < 2; ++a)
; #pragma unroll
;             for (int b = 0; b < 2; ++b)
; #pragma unroll
;                 for (int m = 0; m < 4; ++m)
; #pragma unroll
;                     for (int n = 0; n < 2; ++n) acc[a][b][m][n] = (f32x4){0.f, 0.f, 0.f, 0.f};
.LBB0_137:
	s_ashr_i32 s29, s28, 31
	s_lshl_b64 s[30:31], s[28:29], 21
	s_add_u32 s30, s33, s30
	s_addc_u32 s31, s44, s31
	s_and_b64 s[34:35], s[2:3], exec
	s_cselect_b32 s5, s31, s39
	s_cselect_b32 s18, s30, s38
	s_ashr_i32 s27, s26, 31
	s_lshl_b64 s[34:35], s[26:27], 21
	s_add_u32 s34, s16, s34
	s_addc_u32 s35, s17, s35
	s_and_b64 s[42:43], s[2:3], exec
	s_cselect_b32 s27, s35, s41
	s_cselect_b32 s29, s34, s40
	s_add_u32 s38, s38, 0x100080
	s_addc_u32 s39, s39, 0
	s_add_u32 s64, s40, 0x100
	v_mov_b32_e32 v2, 0
	s_addc_u32 s65, s41, 0
	s_mov_b32 s66, -2
	v_mov_b32_e32 v3, v2
	v_mov_b64_e32 v[4:5], 0
	v_mov_b64_e32 v[6:7], 0
	v_mov_b64_e32 v[8:9], 0
	v_mov_b64_e32 v[18:19], 0
	v_mov_b64_e32 v[20:21], 0
	v_mov_b64_e32 v[22:23], 0
	v_mov_b64_e32 v[24:25], 0
	v_mov_b64_e32 v[34:35], 0
	v_mov_b64_e32 v[36:37], 0
	v_mov_b64_e32 v[38:39], 0
	v_mov_b64_e32 v[40:41], 0
	v_mov_b64_e32 v[50:51], 0
	v_mov_b64_e32 v[52:53], 0
	v_mov_b64_e32 v[54:55], 0
	v_mov_b64_e32 v[56:57], 0
	v_mov_b64_e32 v[10:11], 0
	v_mov_b64_e32 v[12:13], 0
	v_mov_b64_e32 v[14:15], 0
	v_mov_b64_e32 v[16:17], 0
	v_mov_b64_e32 v[26:27], 0
	v_mov_b64_e32 v[28:29], 0
	v_mov_b64_e32 v[30:31], 0
	v_mov_b64_e32 v[32:33], 0
	v_mov_b64_e32 v[42:43], 0
	v_mov_b64_e32 v[44:45], 0
	v_mov_b64_e32 v[46:47], 0
	v_mov_b64_e32 v[48:49], 0
	v_mov_b64_e32 v[58:59], 0
	v_mov_b64_e32 v[60:61], 0
	v_mov_b64_e32 v[62:63], 0
	v_mov_b64_e32 v[64:65], 0
	v_mov_b64_e32 v[66:67], 0
	v_mov_b64_e32 v[68:69], 0
	v_mov_b64_e32 v[70:71], 0
	v_mov_b64_e32 v[72:73], 0
	v_mov_b64_e32 v[82:83], 0
	v_mov_b64_e32 v[84:85], 0
	v_mov_b64_e32 v[86:87], 0
	v_mov_b64_e32 v[88:89], 0
	v_mov_b64_e32 v[98:99], 0
	v_mov_b64_e32 v[100:101], 0
	v_mov_b64_e32 v[102:103], 0
	v_mov_b64_e32 v[104:105], 0
	v_mov_b64_e32 v[114:115], 0
	v_mov_b64_e32 v[116:117], 0
	v_mov_b64_e32 v[118:119], 0
	v_mov_b64_e32 v[120:121], 0
	v_mov_b64_e32 v[74:75], 0
	v_mov_b64_e32 v[76:77], 0
	v_mov_b64_e32 v[78:79], 0
	v_mov_b64_e32 v[80:81], 0
	v_mov_b64_e32 v[90:91], 0
	v_mov_b64_e32 v[92:93], 0
	v_mov_b64_e32 v[94:95], 0
	v_mov_b64_e32 v[96:97], 0
	v_mov_b64_e32 v[106:107], 0
	v_mov_b64_e32 v[108:109], 0
	v_mov_b64_e32 v[110:111], 0
	v_mov_b64_e32 v[112:113], 0
	v_mov_b64_e32 v[122:123], 0
	v_mov_b64_e32 v[124:125], 0
	v_mov_b64_e32 v[126:127], 0
	v_mov_b64_e32 v[128:129], 0

;     __host__ __device__ bool next(int i, Unit& u) const { const bool ok = StaticOrder::next(i >> 1, u); u.z = i & 1; return ok; }
; template <class Epi, class Sched, bool ALIGN_EPI = true, bool SP2 = true>
; __device__ __forceinline__ void gemm_phase(LAS unsigned char* lds, const Gemm g, const Sched& S, const Epi& E) {
;     ...
;         const bool has_next = S.next(ui + 1, nxt);
;         const char* nA = has_next ? PG8_ABASE(nxt) : cA; const char* nB = has_next ? PG8_BBASE(nxt) : cB;
;         for (int t = 0; t < nt; t += 2) {
;             const bool last = (t == nt - 2);
;             const char* a1 = cA + (size_t)(t + 1) * kstep;
;             const char* a2 = last ? nA : cA + (size_t)(t + 2) * kstep; const char* b2 = last ? nB : cB + (size_t)(t + 2) * kstep;
;             const char* a3 = a2 + kstep; const char* b3 = b2 + kstep;
;     ...
;         for (int a = 0; a < 2; ++a)
; #pragma unroll
;             for (int b = 0; b < 2; ++b)
; #pragma unroll
;                 for (int m = 0; m < 4; ++m)
; #pragma unroll
;                     for (int n = 0; n < 2; ++n) acc[a][b][m][n] = (f32x4){0.f, 0.f, 0.f, 0.f};
.LBB0_450:
	s_ashr_i32 s13, s12, 31
	s_lshl_b64 s[14:15], s[12:13], 19
	s_add_u32 s14, s27, s14
	s_addc_u32 s15, s28, s15
	s_and_b64 s[16:17], s[0:1], exec
	s_cselect_b32 s13, s15, s21
	s_cselect_b32 s45, s14, s20
	s_ashr_i32 s11, s10, 31
	s_lshl_b64 s[16:17], s[10:11], 19
	s_add_u32 s16, s29, s16
	s_addc_u32 s17, s30, s17
	s_and_b64 s[24:25], s[0:1], exec
	s_cselect_b32 s11, s17, s23
	s_cselect_b32 s46, s16, s22
	s_add_u32 s20, s20, 0x40080
	s_addc_u32 s21, s21, 0
	s_add_u32 s47, s22, 0x100
	v_mov_b32_e32 v2, 0
	s_addc_u32 s48, s23, 0
	s_mov_b32 s49, -2
	v_mov_b32_e32 v3, v2
	v_mov_b64_e32 v[4:5], 0
	v_mov_b64_e32 v[6:7], 0
	v_mov_b64_e32 v[8:9], 0
	v_mov_b64_e32 v[10:11], 0
	v_mov_b64_e32 v[12:13], 0
	v_mov_b64_e32 v[18:19], 0
	v_mov_b64_e32 v[20:21], 0
	v_mov_b64_e32 v[26:27], 0
	v_mov_b64_e32 v[28:29], 0
	v_mov_b64_e32 v[34:35], 0
	v_mov_b64_e32 v[36:37], 0
	v_mov_b64_e32 v[42:43], 0
	v_mov_b64_e32 v[44:45], 0
	v_mov_b64_e32 v[50:51], 0
	v_mov_b64_e32 v[52:53], 0
	v_mov_b64_e32 v[14:15], 0
	v_mov_b64_e32 v[16:17], 0
	v_mov_b64_e32 v[22:23], 0
	v_mov_b64_e32 v[24:25], 0
	v_mov_b64_e32 v[30:31], 0
	v_mov_b64_e32 v[32:33], 0
	v_mov_b64_e32 v[38:39], 0
	v_mov_b64_e32 v[40:41], 0
	v_mov_b64_e32 v[46:47], 0
	v_mov_b64_e32 v[48:49], 0
	v_mov_b64_e32 v[54:55], 0
	v_mov_b64_e32 v[56:57], 0
	v_mov_b64_e32 v[58:59], 0
	v_mov_b64_e32 v[60:61], 0
	v_mov_b64_e32 v[62:63], 0
	v_mov_b64_e32 v[64:65], 0
	v_mov_b64_e32 v[66:67], 0
	v_mov_b64_e32 v[68:69], 0
	v_mov_b64_e32 v[70:71], 0
	v_mov_b64_e32 v[72:73], 0
	v_mov_b64_e32 v[74:75], 0
	v_mov_b64_e32 v[76:77], 0
	v_mov_b64_e32 v[82:83], 0
	v_mov_b64_e32 v[84:85], 0
	v_mov_b64_e32 v[90:91], 0
	v_mov_b64_e32 v[92:93], 0
	v_mov_b64_e32 v[98:99], 0
	v_mov_b64_e32 v[100:101], 0
	v_mov_b64_e32 v[106:107], 0
	v_mov_b64_e32 v[108:109], 0
	v_mov_b64_e32 v[114:115], 0
	v_mov_b64_e32 v[116:117], 0
	v_mov_b64_e32 v[78:79], 0
	v_mov_b64_e32 v[80:81], 0
	v_mov_b64_e32 v[86:87], 0
	v_mov_b64_e32 v[88:89], 0
	v_mov_b64_e32 v[94:95], 0
	v_mov_b64_e32 v[96:97], 0
	v_mov_b64_e32 v[102:103], 0
	v_mov_b64_e32 v[104:105], 0
	v_mov_b64_e32 v[110:111], 0
	v_mov_b64_e32 v[112:113], 0
	v_mov_b64_e32 v[118:119], 0
	v_mov_b64_e32 v[120:121], 0
	v_mov_b64_e32 v[122:123], 0
	v_mov_b64_e32 v[124:125], 0
	v_mov_b64_e32 v[126:127], 0
	v_mov_b64_e32 v[128:129], 0

;     __host__ __device__ bool next(int i, Unit& u) const { const bool ok = StaticOrder::next(i >> 1, u); u.z = i & 1; return ok; }
; template <class Epi, class Sched, bool ALIGN_EPI = true, bool SP2 = true>
; __device__ __forceinline__ void gemm_phase(LAS unsigned char* lds, const Gemm g, const Sched& S, const Epi& E) {
;     ...
;         const bool has_next = S.next(ui + 1, nxt);
;         const char* nA = has_next ? PG8_ABASE(nxt) : cA; const char* nB = has_next ? PG8_BBASE(nxt) : cB;
;         for (int t = 0; t < nt; t += 2) {
;             const bool last = (t == nt - 2);
;             const char* a1 = cA + (size_t)(t + 1) * kstep;
;             const char* a2 = last ? nA : cA + (size_t)(t + 2) * kstep; const char* b2 = last ? nB : cB + (size_t)(t + 2) * kstep;
;             const char* a3 = a2 + kstep; const char* b3 = b2 + kstep;
;     ...
;         for (int a = 0; a < 2; ++a)
; #pragma unroll
;             for (int b = 0; b < 2; ++b)
; #pragma unroll
;                 for (int m = 0; m < 4; ++m)
; #pragma unroll
;                     for (int n = 0; n < 2; ++n) acc[a][b][m][n] = (f32x4){0.f, 0.f, 0.f, 0.f};
;         cur = nxt; cA = nA; cB = nB; ++ui;
.LBB0_1459:
	s_ashr_i32 s25, s24, 31
	s_and_b32 s60, s59, 1
	s_lshl_b64 s[26:27], s[24:25], 20
	s_cmp_eq_u32 s60, 0
	s_cselect_b32 s25, s33, s48
	s_cselect_b32 s23, s40, s49
	s_cselect_b32 s38, s41, s50
	s_cselect_b32 s39, s42, s51
	s_add_u32 s26, s25, s26
	s_addc_u32 s27, s23, s27
	s_and_b64 s[28:29], s[0:1], exec
	s_cselect_b32 s25, s27, s35
	s_cselect_b32 s31, s26, s34
	s_ashr_i32 s23, s22, 31
	s_lshl_b64 s[28:29], s[22:23], 20
	s_add_u32 s28, s38, s28
	s_addc_u32 s29, s39, s29
	s_and_b64 s[38:39], s[0:1], exec
	s_cselect_b32 s23, s29, s37
	s_cselect_b32 s61, s28, s36
	s_add_u32 s34, s34, 0x80080
	s_addc_u32 s35, s35, 0
	s_add_u32 s62, s36, 0x100
	v_mov_b32_e32 v2, 0
	s_addc_u32 s63, s37, 0
	s_mov_b32 s64, -2
	v_mov_b32_e32 v3, v2
	v_mov_b64_e32 v[4:5], 0
	v_mov_b64_e32 v[6:7], 0
	v_mov_b64_e32 v[8:9], 0
	v_mov_b64_e32 v[18:19], 0
	v_mov_b64_e32 v[20:21], 0
	v_mov_b64_e32 v[22:23], 0
	v_mov_b64_e32 v[24:25], 0
	v_mov_b64_e32 v[34:35], 0
	v_mov_b64_e32 v[36:37], 0
	v_mov_b64_e32 v[38:39], 0
	v_mov_b64_e32 v[40:41], 0
	v_mov_b64_e32 v[50:51], 0
	v_mov_b64_e32 v[52:53], 0
	v_mov_b64_e32 v[54:55], 0
	v_mov_b64_e32 v[56:57], 0
	v_mov_b64_e32 v[10:11], 0
	v_mov_b64_e32 v[12:13], 0
	v_mov_b64_e32 v[14:15], 0
	v_mov_b64_e32 v[16:17], 0
	v_mov_b64_e32 v[26:27], 0
	v_mov_b64_e32 v[28:29], 0
	v_mov_b64_e32 v[30:31], 0
	v_mov_b64_e32 v[32:33], 0
	v_mov_b64_e32 v[42:43], 0
	v_mov_b64_e32 v[44:45], 0
	v_mov_b64_e32 v[46:47], 0
	v_mov_b64_e32 v[48:49], 0
	v_mov_b64_e32 v[58:59], 0
	v_mov_b64_e32 v[60:61], 0
	v_mov_b64_e32 v[62:63], 0
	v_mov_b64_e32 v[64:65], 0
	v_mov_b64_e32 v[66:67], 0
	v_mov_b64_e32 v[68:69], 0
	v_mov_b64_e32 v[70:71], 0
	v_mov_b64_e32 v[72:73], 0
	v_mov_b64_e32 v[82:83], 0
	v_mov_b64_e32 v[84:85], 0
	v_mov_b64_e32 v[86:87], 0
	v_mov_b64_e32 v[88:89], 0
	v_mov_b64_e32 v[98:99], 0
	v_mov_b64_e32 v[100:101], 0
	v_mov_b64_e32 v[102:103], 0
	v_mov_b64_e32 v[104:105], 0
	v_mov_b64_e32 v[122:123], 0
	v_mov_b64_e32 v[124:125], 0
	v_mov_b64_e32 v[126:127], 0
	v_mov_b64_e32 v[128:129], 0
	v_mov_b64_e32 v[74:75], 0
	v_mov_b64_e32 v[76:77], 0
	v_mov_b64_e32 v[78:79], 0
	v_mov_b64_e32 v[80:81], 0
	v_mov_b64_e32 v[90:91], 0
	v_mov_b64_e32 v[92:93], 0
	v_mov_b64_e32 v[94:95], 0
	v_mov_b64_e32 v[96:97], 0
	v_mov_b64_e32 v[106:107], 0
	v_mov_b64_e32 v[108:109], 0
	v_mov_b64_e32 v[110:111], 0
	v_mov_b64_e32 v[112:113], 0
	v_mov_b64_e32 v[138:139], 0
	v_mov_b64_e32 v[140:141], 0
	s_waitcnt vmcnt(0)
	v_mov_b32_e32 v146, v2
	v_mov_b32_e32 v147, v2
	v_mov_b32_e32 v148, v2
	v_mov_b32_e32 v149, v2

;     __host__ __device__ bool next(int i, Unit& u) const { const bool ok = StaticOrder::next(i >> 1, u); u.z = i & 1; return ok; }
; template <class Epi, class Sched, bool ALIGN_EPI = true, bool SP2 = true>
; __device__ __forceinline__ void gemm_phase(LAS unsigned char* lds, const Gemm g, const Sched& S, const Epi& E) {
;     ...
;         const bool has_next = S.next(ui + 1, nxt);
;         const char* nA = has_next ? PG8_ABASE(nxt) : cA; const char* nB = has_next ? PG8_BBASE(nxt) : cB;
;         for (int t = 0; t < nt; t += 2) {
;             const bool last = (t == nt - 2);
;             const char* a1 = cA + (size_t)(t + 1) * kstep;
;             const char* a2 = last ? nA : cA + (size_t)(t + 2) * kstep; const char* b2 = last ? nB : cB + (size_t)(t + 2) * kstep;
;             const char* a3 = a2 + kstep; const char* b3 = b2 + kstep;
;     ...
;         for (int a = 0; a < 2; ++a)
; #pragma unroll
;             for (int b = 0; b < 2; ++b)
; #pragma unroll
;                 for (int m = 0; m < 4; ++m)
; #pragma unroll
;                     for (int n = 0; n < 2; ++n) acc[a][b][m][n] = (f32x4){0.f, 0.f, 0.f, 0.f};
.LBB0_1638:
	s_ashr_i32 s43, s42, 31
	s_lshl_b64 s[44:45], s[42:43], 21
	s_add_u32 s44, s10, s44
	s_addc_u32 s45, s11, s45
	s_and_b64 s[46:47], s[2:3], exec
	s_cselect_b32 s43, s45, s53
	s_cselect_b32 s49, s44, s52
	s_ashr_i32 s41, s40, 31
	s_lshl_b64 s[46:47], s[40:41], 21
	s_add_u32 s46, s12, s46
	s_addc_u32 s47, s13, s47
	s_and_b64 s[56:57], s[2:3], exec
	s_cselect_b32 s41, s47, s55
	s_cselect_b32 s71, s46, s54
	s_add_u32 s52, s52, 0x100080
	s_addc_u32 s53, s53, 0
	s_add_u32 s72, s54, 0x100
	v_mov_b32_e32 v2, 0
	s_addc_u32 s73, s55, 0
	s_mov_b32 s74, -2
	v_mov_b32_e32 v3, v2
	v_mov_b64_e32 v[4:5], 0
	v_mov_b64_e32 v[6:7], 0
	v_mov_b64_e32 v[8:9], 0
	v_mov_b64_e32 v[18:19], 0
	v_mov_b64_e32 v[20:21], 0
	v_mov_b64_e32 v[22:23], 0
	v_mov_b64_e32 v[24:25], 0
	v_mov_b64_e32 v[34:35], 0
	v_mov_b64_e32 v[36:37], 0
	v_mov_b64_e32 v[38:39], 0
	v_mov_b64_e32 v[40:41], 0
	v_mov_b64_e32 v[50:51], 0
	v_mov_b64_e32 v[52:53], 0
	v_mov_b64_e32 v[54:55], 0
	v_mov_b64_e32 v[56:57], 0
	v_mov_b64_e32 v[10:11], 0
	v_mov_b64_e32 v[12:13], 0
	v_mov_b64_e32 v[14:15], 0
	v_mov_b64_e32 v[16:17], 0
	v_mov_b64_e32 v[26:27], 0
	v_mov_b64_e32 v[28:29], 0
	v_mov_b64_e32 v[30:31], 0
	v_mov_b64_e32 v[32:33], 0
	v_mov_b64_e32 v[42:43], 0
	v_mov_b64_e32 v[44:45], 0
	v_mov_b64_e32 v[46:47], 0
	v_mov_b64_e32 v[48:49], 0
	v_mov_b64_e32 v[58:59], 0
	v_mov_b64_e32 v[60:61], 0
	v_mov_b64_e32 v[62:63], 0
	v_mov_b64_e32 v[64:65], 0
	v_mov_b64_e32 v[66:67], 0
	v_mov_b64_e32 v[68:69], 0
	v_mov_b64_e32 v[70:71], 0
	v_mov_b64_e32 v[72:73], 0
	v_mov_b64_e32 v[82:83], 0
	v_mov_b64_e32 v[84:85], 0
	v_mov_b64_e32 v[86:87], 0
	v_mov_b64_e32 v[88:89], 0
	v_mov_b64_e32 v[98:99], 0
	v_mov_b64_e32 v[100:101], 0
	v_mov_b64_e32 v[102:103], 0
	v_mov_b64_e32 v[104:105], 0
	v_mov_b64_e32 v[114:115], 0
	v_mov_b64_e32 v[116:117], 0
	v_mov_b64_e32 v[118:119], 0
	v_mov_b64_e32 v[120:121], 0
	v_mov_b64_e32 v[74:75], 0
	v_mov_b64_e32 v[76:77], 0
	v_mov_b64_e32 v[78:79], 0
	v_mov_b64_e32 v[80:81], 0
	v_mov_b64_e32 v[90:91], 0
	v_mov_b64_e32 v[92:93], 0
	v_mov_b64_e32 v[94:95], 0
	v_mov_b64_e32 v[96:97], 0
	v_mov_b64_e32 v[106:107], 0
	v_mov_b64_e32 v[108:109], 0
	v_mov_b64_e32 v[110:111], 0
	v_mov_b64_e32 v[112:113], 0
	v_mov_b64_e32 v[122:123], 0
	v_mov_b64_e32 v[124:125], 0
	v_mov_b64_e32 v[126:127], 0
	v_mov_b64_e32 v[128:129], 0
	s_waitcnt vmcnt(0)

;     __host__ __device__ bool next(int i, Unit& u) const { const bool ok = StaticOrder::next(i >> 1, u); u.z = i & 1; return ok; }
; template <class Epi, class Sched, bool ALIGN_EPI = true, bool SP2 = true>
; __device__ __forceinline__ void gemm_phase(LAS unsigned char* lds, const Gemm g, const Sched& S, const Epi& E) {
;     ...
;         const bool has_next = S.next(ui + 1, nxt);
;         const char* nA = has_next ? PG8_ABASE(nxt) : cA; const char* nB = has_next ? PG8_BBASE(nxt) : cB;
;         for (int t = 0; t < nt; t += 2) {
;             const bool last = (t == nt - 2);
;             const char* a1 = cA + (size_t)(t + 1) * kstep;
;             const char* a2 = last ? nA : cA + (size_t)(t + 2) * kstep; const char* b2 = last ? nB : cB + (size_t)(t + 2) * kstep;
;             const char* a3 = a2 + kstep; const char* b3 = b2 + kstep;
;     ...
;         for (int a = 0; a < 2; ++a)
; #pragma unroll
;             for (int b = 0; b < 2; ++b)
; #pragma unroll
;                 for (int m = 0; m < 4; ++m)
; #pragma unroll
;                     for (int n = 0; n < 2; ++n) acc[a][b][m][n] = (f32x4){0.f, 0.f, 0.f, 0.f};
.LBB0_1809:
	s_ashr_i32 s25, s24, 31
	s_lshl_b64 s[26:27], s[24:25], 21
	s_add_u32 s26, s33, s26
	s_addc_u32 s27, s36, s27
	s_and_b64 s[28:29], s[0:1], exec
	s_cselect_b32 s25, s27, s5
	s_cselect_b32 s52, s26, s4
	s_ashr_i32 s23, s22, 31
	s_lshl_b64 s[28:29], s[22:23], 21
	s_add_u32 s28, s12, s28
	s_addc_u32 s29, s13, s29
	s_and_b64 s[34:35], s[0:1], exec
	s_cselect_b32 s23, s29, s31
	s_cselect_b32 s53, s28, s30
	s_add_u32 s4, s4, 0x100080
	s_addc_u32 s5, s5, 0
	s_add_u32 s54, s30, 0x100
	v_mov_b32_e32 v2, 0
	s_addc_u32 s55, s31, 0
	s_mov_b32 s56, -2
	v_mov_b32_e32 v3, v2
	v_mov_b64_e32 v[4:5], 0
	v_mov_b64_e32 v[6:7], 0
	v_mov_b64_e32 v[8:9], 0
	v_mov_b64_e32 v[18:19], 0
	v_mov_b64_e32 v[20:21], 0
	v_mov_b64_e32 v[22:23], 0
	v_mov_b64_e32 v[24:25], 0
	v_mov_b64_e32 v[34:35], 0
	v_mov_b64_e32 v[36:37], 0
	v_mov_b64_e32 v[38:39], 0
	v_mov_b64_e32 v[40:41], 0
	v_mov_b64_e32 v[50:51], 0
	v_mov_b64_e32 v[52:53], 0
	v_mov_b64_e32 v[54:55], 0
	v_mov_b64_e32 v[56:57], 0
	v_mov_b64_e32 v[10:11], 0
	v_mov_b64_e32 v[12:13], 0
	v_mov_b64_e32 v[14:15], 0
	v_mov_b64_e32 v[16:17], 0
	v_mov_b64_e32 v[26:27], 0
	v_mov_b64_e32 v[28:29], 0
	v_mov_b64_e32 v[30:31], 0
	v_mov_b64_e32 v[32:33], 0
	v_mov_b64_e32 v[42:43], 0
	v_mov_b64_e32 v[44:45], 0
	v_mov_b64_e32 v[46:47], 0
	v_mov_b64_e32 v[48:49], 0
	v_mov_b64_e32 v[58:59], 0
	v_mov_b64_e32 v[60:61], 0
	v_mov_b64_e32 v[62:63], 0
	v_mov_b64_e32 v[64:65], 0
	v_mov_b64_e32 v[66:67], 0
	v_mov_b64_e32 v[68:69], 0
	v_mov_b64_e32 v[70:71], 0
	v_mov_b64_e32 v[72:73], 0
	v_mov_b64_e32 v[82:83], 0
	v_mov_b64_e32 v[84:85], 0
	v_mov_b64_e32 v[86:87], 0
	v_mov_b64_e32 v[88:89], 0
	v_mov_b64_e32 v[98:99], 0
	v_mov_b64_e32 v[100:101], 0
	v_mov_b64_e32 v[102:103], 0
	v_mov_b64_e32 v[104:105], 0
	v_mov_b64_e32 v[114:115], 0
	v_mov_b64_e32 v[116:117], 0
	v_mov_b64_e32 v[118:119], 0
	v_mov_b64_e32 v[120:121], 0
	v_mov_b64_e32 v[74:75], 0
	v_mov_b64_e32 v[76:77], 0
	v_mov_b64_e32 v[78:79], 0
	v_mov_b64_e32 v[80:81], 0
	v_mov_b64_e32 v[90:91], 0
	v_mov_b64_e32 v[92:93], 0
	v_mov_b64_e32 v[94:95], 0
	v_mov_b64_e32 v[96:97], 0
	v_mov_b64_e32 v[106:107], 0
	v_mov_b64_e32 v[108:109], 0
	v_mov_b64_e32 v[110:111], 0
	v_mov_b64_e32 v[112:113], 0
	v_mov_b64_e32 v[122:123], 0
	v_mov_b64_e32 v[124:125], 0
	v_mov_b64_e32 v[126:127], 0
	v_mov_b64_e32 v[128:129], 0

; template <class Epi, class Sched, bool ALIGN_EPI = true, bool SP2 = true>
; __device__ __forceinline__ void gemm_phase(LAS unsigned char* lds, const Gemm g, const Sched& S, const Epi& E) {
;     ...
;         const char* nA = has_next ? PG8_ABASE(nxt) : cA; const char* nB = has_next ? PG8_BBASE(nxt) : cB;
;         for (int t = 0; t < nt; t += 2) {
;             const bool last = (t == nt - 2);
;             const char* a1 = cA + (size_t)(t + 1) * kstep;
;             const char* a2 = last ? nA : cA + (size_t)(t + 2) * kstep; const char* b2 = last ? nB : cB + (size_t)(t + 2) * kstep;
;             const char* a3 = a2 + kstep; const char* b3 = b2 + kstep;
;     ...
;         for (int a = 0; a < 2; ++a)
; #pragma unroll
;             for (int b = 0; b < 2; ++b)
; #pragma unroll
;                 for (int m = 0; m < 4; ++m)
; #pragma unroll
;                     for (int n = 0; n < 2; ++n) acc[a][b][m][n] = (f32x4){0.f, 0.f, 0.f, 0.f};
.LBB0_2059:
	s_add_u32 s24, s24, 0x2b0080
	s_addc_u32 s25, s25, 0
	s_add_u32 s51, s26, 0x100
	v_mov_b32_e32 v2, 0
	s_addc_u32 s52, s27, 0
	s_mov_b32 s53, -2
	v_mov_b32_e32 v3, v2
	v_mov_b64_e32 v[4:5], 0
	v_mov_b64_e32 v[6:7], 0
	v_mov_b64_e32 v[8:9], 0
	v_mov_b64_e32 v[18:19], 0
	v_mov_b64_e32 v[20:21], 0
	v_mov_b64_e32 v[22:23], 0
	v_mov_b64_e32 v[24:25], 0
	v_mov_b64_e32 v[34:35], 0
	v_mov_b64_e32 v[36:37], 0
	v_mov_b64_e32 v[38:39], 0
	v_mov_b64_e32 v[40:41], 0
	v_mov_b64_e32 v[50:51], 0
	v_mov_b64_e32 v[52:53], 0
	v_mov_b64_e32 v[54:55], 0
	v_mov_b64_e32 v[56:57], 0
	v_mov_b64_e32 v[10:11], 0
	v_mov_b64_e32 v[12:13], 0
	v_mov_b64_e32 v[14:15], 0
	v_mov_b64_e32 v[16:17], 0
	v_mov_b64_e32 v[26:27], 0
	v_mov_b64_e32 v[28:29], 0
	v_mov_b64_e32 v[30:31], 0
	v_mov_b64_e32 v[32:33], 0
	v_mov_b64_e32 v[42:43], 0
	v_mov_b64_e32 v[44:45], 0
	v_mov_b64_e32 v[46:47], 0
	v_mov_b64_e32 v[48:49], 0
	v_mov_b64_e32 v[58:59], 0
	v_mov_b64_e32 v[60:61], 0
	v_mov_b64_e32 v[62:63], 0
	v_mov_b64_e32 v[64:65], 0
	v_mov_b64_e32 v[66:67], 0
	v_mov_b64_e32 v[68:69], 0
	v_mov_b64_e32 v[70:71], 0
	v_mov_b64_e32 v[72:73], 0
	v_mov_b64_e32 v[82:83], 0
	v_mov_b64_e32 v[84:85], 0
	v_mov_b64_e32 v[86:87], 0
	v_mov_b64_e32 v[88:89], 0
	v_mov_b64_e32 v[98:99], 0
	v_mov_b64_e32 v[100:101], 0
	v_mov_b64_e32 v[102:103], 0
	v_mov_b64_e32 v[104:105], 0
	v_mov_b64_e32 v[114:115], 0
	v_mov_b64_e32 v[116:117], 0
	v_mov_b64_e32 v[118:119], 0
	v_mov_b64_e32 v[120:121], 0
	v_mov_b64_e32 v[74:75], 0
	v_mov_b64_e32 v[76:77], 0
	v_mov_b64_e32 v[78:79], 0
	v_mov_b64_e32 v[80:81], 0
	v_mov_b64_e32 v[90:91], 0
	v_mov_b64_e32 v[92:93], 0
	v_mov_b64_e32 v[94:95], 0
	v_mov_b64_e32 v[96:97], 0
	v_mov_b64_e32 v[106:107], 0
	v_mov_b64_e32 v[108:109], 0
	v_mov_b64_e32 v[110:111], 0
	v_mov_b64_e32 v[112:113], 0
	v_mov_b64_e32 v[122:123], 0
	v_mov_b64_e32 v[124:125], 0
	v_mov_b64_e32 v[126:127], 0
	v_mov_b64_e32 v[128:129], 0

;     __host__ __device__ bool next(int i, Unit& u) const { const bool ok = StaticOrder::next(i >> 1, u); u.z = i & 1; return ok; }
; template <class Epi, class Sched, bool ALIGN_EPI = true, bool SP2 = true>
; __device__ __forceinline__ void gemm_phase(LAS unsigned char* lds, const Gemm g, const Sched& S, const Epi& E) {
;     ...
;         const bool has_next = S.next(ui + 1, nxt);
;         const char* nA = has_next ? PG8_ABASE(nxt) : cA; const char* nB = has_next ? PG8_BBASE(nxt) : cB;
;         for (int t = 0; t < nt; t += 2) {
;             const bool last = (t == nt - 2);
;             const char* a1 = cA + (size_t)(t + 1) * kstep;
;             const char* a2 = last ? nA : cA + (size_t)(t + 2) * kstep; const char* b2 = last ? nB : cB + (size_t)(t + 2) * kstep;
;             const char* a3 = a2 + kstep; const char* b3 = b2 + kstep;
;     ...
;         for (int a = 0; a < 2; ++a)
; #pragma unroll
;             for (int b = 0; b < 2; ++b)
; #pragma unroll
;                 for (int m = 0; m < 4; ++m)
; #pragma unroll
;                     for (int n = 0; n < 2; ++n) acc[a][b][m][n] = (f32x4){0.f, 0.f, 0.f, 0.f};
.LBB0_2099:
	s_ashr_i32 s15, s14, 31
	s_lshl_b64 s[16:17], s[14:15], 17
	s_add_u32 s16, s42, s16
	s_addc_u32 s17, s43, s17
	s_and_b64 s[18:19], s[0:1], exec
	s_cselect_b32 s15, s17, s25
	s_cselect_b32 s57, s16, s24
	s_ashr_i32 s13, s12, 31
	s_lshl_b64 s[18:19], s[12:13], 17
	s_add_u32 s18, s44, s18
	s_addc_u32 s19, s45, s19
	s_and_b64 s[26:27], s[0:1], exec
	v_mov_b32_e32 v2, 0
	s_cselect_b32 s13, s19, s23
	s_cselect_b32 s58, s18, s22
	s_mov_b32 s30, 0
	s_mov_b64 s[26:27], -1
	s_mov_b64 s[28:29], 0
	v_mov_b32_e32 v3, v2
	v_mov_b64_e32 v[4:5], 0
	v_mov_b64_e32 v[6:7], 0
	v_mov_b64_e32 v[8:9], 0
	v_mov_b64_e32 v[10:11], 0
	v_mov_b64_e32 v[12:13], 0
	v_mov_b64_e32 v[18:19], 0
	v_mov_b64_e32 v[20:21], 0
	v_mov_b64_e32 v[26:27], 0
	v_mov_b64_e32 v[28:29], 0
	v_mov_b64_e32 v[34:35], 0
	v_mov_b64_e32 v[36:37], 0
	v_mov_b64_e32 v[42:43], 0
	v_mov_b64_e32 v[44:45], 0
	v_mov_b64_e32 v[50:51], 0
	v_mov_b64_e32 v[52:53], 0
	v_mov_b64_e32 v[14:15], 0
	v_mov_b64_e32 v[16:17], 0
	v_mov_b64_e32 v[22:23], 0
	v_mov_b64_e32 v[24:25], 0
	v_mov_b64_e32 v[30:31], 0
	v_mov_b64_e32 v[32:33], 0
	v_mov_b64_e32 v[38:39], 0
	v_mov_b64_e32 v[40:41], 0
	v_mov_b64_e32 v[46:47], 0
	v_mov_b64_e32 v[48:49], 0
	v_mov_b64_e32 v[54:55], 0
	v_mov_b64_e32 v[56:57], 0
	v_mov_b64_e32 v[58:59], 0
	v_mov_b64_e32 v[60:61], 0
	v_mov_b64_e32 v[62:63], 0
	v_mov_b64_e32 v[64:65], 0
	v_mov_b64_e32 v[66:67], 0
	v_mov_b64_e32 v[68:69], 0
	v_mov_b64_e32 v[70:71], 0
	v_mov_b64_e32 v[72:73], 0
	v_mov_b64_e32 v[74:75], 0
	v_mov_b64_e32 v[76:77], 0
	v_mov_b64_e32 v[82:83], 0
	v_mov_b64_e32 v[84:85], 0
	v_mov_b64_e32 v[90:91], 0
	v_mov_b64_e32 v[92:93], 0
	v_mov_b64_e32 v[98:99], 0
	v_mov_b64_e32 v[100:101], 0
	v_mov_b64_e32 v[106:107], 0
	v_mov_b64_e32 v[108:109], 0
	v_mov_b64_e32 v[114:115], 0
	v_mov_b64_e32 v[116:117], 0
	v_mov_b64_e32 v[78:79], 0
	v_mov_b64_e32 v[80:81], 0
	v_mov_b64_e32 v[86:87], 0
	v_mov_b64_e32 v[88:89], 0
	v_mov_b64_e32 v[94:95], 0
	v_mov_b64_e32 v[96:97], 0
	v_mov_b64_e32 v[102:103], 0
	v_mov_b64_e32 v[104:105], 0
	v_mov_b64_e32 v[110:111], 0
	v_mov_b64_e32 v[112:113], 0
	v_mov_b64_e32 v[118:119], 0
	v_mov_b64_e32 v[120:121], 0
	v_mov_b64_e32 v[122:123], 0
	v_mov_b64_e32 v[124:125], 0
	v_mov_b64_e32 v[126:127], 0
	v_mov_b64_e32 v[128:129], 0
